# gate/up GEMM: workgroups that run one tile fewer start 0/5/10/15 us late so the epilogue store bursts of the grid do not coincide
# baseline (speedup 1.0000x reference)
; #define LAS __attribute__((address_space(3)))
; #define PG8_WAIT_V(n) asm volatile("s_waitcnt vmcnt(" #n ")" ::: "memory")
; #define PG8_BAR __builtin_amdgcn_s_barrier()
; __device__ __forceinline__ bool get_unit(LAS unsigned char* lds, int i, Unit& u) {
;     if (i >= 16) return false;
;     const LAS int* e = (const LAS int*)(lds + 131072 + 64) + 8 * i;
;     const int valid = __builtin_amdgcn_readfirstlane(e[0]);
;     u.pm = __builtin_amdgcn_readfirstlane(e[1]); u.pn = __builtin_amdgcn_readfirstlane(e[2]); u.sub = __builtin_amdgcn_readfirstlane(e[3]);
;     u.kt0 = __builtin_amdgcn_readfirstlane(e[4]); u.nt = __builtin_amdgcn_readfirstlane(e[5]); u.sp = __builtin_amdgcn_readfirstlane(e[6]);
;     return valid != 0;
; }
; template <class Epi>
; __device__ __forceinline__ void gemm_phase(LAS unsigned char* lds, const Gemm g, const Epi& E) {
;     ...
;     for (int i = 0; i < 2; ++i) { int R, C; stage_rc(tid * 16 + i * 8192, R, C); voffA[i] = (unsigned)(R * K + C) * 2u; }
;     const size_t kstep = (size_t)(BK * 2);
;     const size_t hstep = (size_t)HALF * K * 2;
;     const size_t tstep = 2 * hstep;
;     const unsigned ldsw = (unsigned)wid * 1024u;
;     const int aoff = lds_byte(wr * 64 + fr, fq * 8), boff = lds_byte(wc * 32 + fr, fq * 8);
;     ...
;     Unit cur; int ui = 0;
;     if (!get_unit(lds, 0, cur)) return;
;     f32x4 acc[2][2][4][2];
; #pragma unroll
;     for (int a = 0; a < 2; ++a)
; #pragma unroll
;         for (int b = 0; b < 2; ++b)
; #pragma unroll
;             for (int m = 0; m < 4; ++m)
; #pragma unroll
;                 for (int n = 0; n < 2; ++n) acc[a][b][m][n] = (f32x4){0.f, 0.f, 0.f, 0.f};
;     bf16x8 At[4][2], B0[2][2], B1[2][2];
;     const char* cA = (const char*)((cur.sub & 1) ? g.A1 : g.A0) + (size_t)cur.pm * tstep + (size_t)cur.kt0 * kstep; const char* cB = (const char*)((cur.sub & 1) ? g.B1 : g.B0) + (size_t)cur.pn * tstep + (size_t)cur.kt0 * kstep;
;     PG8_STAGE(PG8_SB(0, 0), cB, voffA); PG8_STAGE(PG8_SB(0, 1), cB + hstep, voffA); PG8_STAGE(PG8_SA(0, 0), cA, voffA); PG8_STAGE(PG8_SA(0, 1), cA + hstep, voffA);
;     if (wr == 1) PG8_BAR;
;     PG8_WAIT_V(2); PG8_BAR;
;     PG8_STAGE(PG8_SB(1, 0), cB + kstep, voffA); PG8_STAGE(PG8_SA(1, 0), cA + kstep, voffA); PG8_STAGE(PG8_SB(1, 1), cB + hstep + kstep, voffA);
.LBB0_431:
	s_or_b64 exec, exec, s[4:5]
	v_readlane_b32 s98, v254, 21
	s_cmp_eq_u32 s27, 10
	s_cselect_b64 s[100:101], -1, 0
	v_readlane_b32 s2, v254, 22
	v_readlane_b32 s99, v254, 23
	s_nop 1
	s_and_b32 s100, s100, s2
	s_and_b32 s101, s101, s99
	s_cmp_lg_u64 s[100:101], 0
	s_cselect_b32 s99, 0x80, 48
	s_cmp_lt_u32 s98, s99
	s_cbranch_scc1 .Lgu_nodelay
	s_and_b32 s98, s98, 3
	s_cmp_eq_u32 s98, 0
	s_cbranch_scc1 .Lgu_nodelay
.Lgu_dly:
	s_sleep 127
	s_sleep 36
	s_add_i32 s98, s98, -1
	s_cmp_lg_u32 s98, 0
	s_cbranch_scc1 .Lgu_dly
.Lgu_nodelay:
	s_add_i32 s2, 0, 0x20040
	v_mov_b32_e32 v10, v138
	v_mov_b32_e32 v0, s2
	v_readlane_b32 s2, v254, 14
	s_waitcnt vmcnt(0) lgkmcnt(0)
	s_barrier
	ds_read_b96 v[2:4], v0
	v_mov_b32_e32 v0, s2
	ds_read_b64 v[6:7], v0
	v_readfirstlane_b32 s12, v10
	s_waitcnt lgkmcnt(1)
	v_readfirstlane_b32 s2, v2
	v_readfirstlane_b32 s6, v3
	v_readfirstlane_b32 s8, v4
	s_waitcnt lgkmcnt(0)
	v_readfirstlane_b32 s4, v6
	s_cmp_eq_u32 s2, 0
	v_readfirstlane_b32 s37, v7
	s_cbranch_scc1 .LBB0_451
	v_lshlrev_b32_e32 v0, 4, v10
	v_add_u32_e32 v2, 0x2000, v0
	v_ashrrev_i32_e32 v3, 31, v2
	v_lshrrev_b32_e32 v3, 22, v3
	v_add_u32_e32 v3, v2, v3
	v_ashrrev_i32_e32 v11, 10, v3
	v_mul_i32_i24_e32 v4, 0x400, v11
	v_sub_u32_e32 v2, v2, v4
	v_lshrrev_b32_e32 v4, 4, v2
	v_bitop3_b32 v2, v4, v2, 32 bitop3:0x6c
	v_ashrrev_i32_e32 v4, 31, v2
	v_lshrrev_b32_e32 v4, 26, v4
	v_add_u32_e32 v4, v2, v4
	v_ashrrev_i32_e32 v12, 6, v4
	v_and_b32_e32 v4, 0xc0, v4
	v_sub_u32_e32 v2, v2, v4
	v_lshlrev_b32_e32 v3, 5, v11
	v_ashrrev_i16_sdwa v2, v173, sext(v2) dst_sel:DWORD dst_unused:UNUSED_PAD src0_sel:DWORD src1_sel:BYTE_0
	v_and_b32_e32 v3, 32, v3
	v_bfe_i32 v13, v2, 0, 16
	v_add_u32_e32 v2, v3, v13
	v_lshlrev_b32_e32 v3, 3, v11
	v_and_b32_e32 v3, 0x1ffff0, v3
	v_add_lshl_u32 v3, v12, v3, 11
	v_lshl_add_u32 v130, v2, 1, v3
	v_bfe_i32 v3, v10, 27, 1
	v_lshrrev_b32_e32 v3, 22, v3
	v_add_u32_e32 v3, v0, v3
	v_and_b32_e32 v3, 0xfffffc00, v3
	v_sub_u32_e32 v0, v0, v3
	v_lshrrev_b32_e32 v3, 4, v0
	s_ashr_i32 s13, s12, 6
	v_bitop3_b32 v0, v3, v0, 32 bitop3:0x6c
	s_ashr_i32 s14, s12, 8
	s_lshl_b32 s2, s13, 10
	v_ashrrev_i32_e32 v3, 31, v0
	s_cmp_eq_u32 s27, 1
	s_mov_b32 s5, 0x1c8000
	v_ashrrev_i32_e32 v2, 31, v10
	v_lshrrev_b32_e32 v3, 26, v3
	s_cselect_b32 s5, s5, 0x1248000
	v_lshrrev_b32_e32 v2, 26, v2
	v_add_u32_e32 v3, v0, v3
	s_add_u32 s20, s30, s5
	v_add_u32_e32 v2, v10, v2
	v_ashrrev_i32_e32 v15, 6, v3
	v_and_b32_e32 v3, 0xc0, v3
	s_addc_u32 s26, s31, 0
	v_ashrrev_i32_e32 v14, 6, v2
	v_sub_u32_e32 v0, v0, v3
	s_ashr_i32 s7, s6, 31
	s_ashr_i32 s5, s4, 31
	s_ashr_i32 s9, s8, 31
	v_lshlrev_b32_e32 v2, 5, v14
	v_ashrrev_i16_sdwa v0, v173, sext(v0) dst_sel:DWORD dst_unused:UNUSED_PAD src0_sel:DWORD src1_sel:BYTE_0
	s_lshl_b64 s[10:11], s[6:7], 19
	s_lshl_b64 s[52:53], s[4:5], 7
	s_lshl_b64 s[4:5], s[8:9], 19
	v_and_b32_e32 v2, 32, v2
	v_bfe_i32 v16, v0, 0, 16
	s_add_u32 s4, s20, s4
	v_add_u32_e32 v0, v2, v16
	v_lshlrev_b32_e32 v2, 3, v14
	s_addc_u32 s5, s26, s5
	v_and_b32_e32 v2, 0x1ffff0, v2
	s_add_u32 s4, s4, s52
	v_add_lshl_u32 v2, v15, v2, 11
	s_addc_u32 s5, s5, s53
	s_add_i32 s7, s2, 0
	v_lshl_add_u32 v0, v0, 1, v2
	s_add_i32 m0, s7, 0x10000
	v_writelane_b32 v254, s60, 30
	global_load_lds_dwordx4 v0, s[4:5]
	s_add_i32 m0, s7, 0x12000
	s_add_u32 s9, s35, s10
	s_addc_u32 s15, s28, s11
	s_add_u32 s10, s4, 0x40000
	global_load_lds_dwordx4 v130, s[4:5]
	s_addc_u32 s11, s5, 0
	s_add_i32 m0, s7, 0x14000
	v_writelane_b32 v254, s61, 31
	global_load_lds_dwordx4 v0, s[10:11]
	s_add_i32 m0, s7, 0x16000
	s_mov_b32 s60, s68
	s_add_u32 s68, s9, s52
	s_addc_u32 s69, s15, s53
	s_add_i32 s9, s7, 0x2000
	global_load_lds_dwordx4 v130, s[10:11]
	s_mov_b32 m0, s7
	s_add_u32 s10, s68, 0x40000
	global_load_lds_dwordx4 v0, s[68:69]
	s_mov_b32 m0, s9
	s_addc_u32 s11, s69, 0
	s_add_i32 s45, s7, 0x4000
	global_load_lds_dwordx4 v130, s[68:69]
	s_mov_b32 m0, s45
	s_add_i32 s52, s7, 0x6000
	global_load_lds_dwordx4 v0, s[10:11]
	s_mov_b32 m0, s52
	v_mov_b32_e32 v131, v1
	global_load_lds_dwordx4 v130, s[10:11]
	s_cmp_eq_u32 s14, 1
	v_lshl_add_u64 v[8:9], s[4:5], 0, v[0:1]
	v_lshl_add_u64 v[6:7], s[4:5], 0, v[130:131]
	v_lshl_add_u64 v[2:3], s[68:69], 0, v[0:1]
	s_cselect_b64 s[10:11], -1, 0
	s_cmp_lg_u32 s14, 1
	v_lshl_add_u64 v[4:5], s[68:69], 0, v[130:131]
	s_cbranch_scc1 .LBB0_434
	s_barrier
